# phase14 top-16 selection by radix select instead of rank loops; phase14-15 grid barrier replaced by workgroup barrier; tile-0 K/V DMA issued at tile start
# speedup vs baseline: 1.0529x; 1.0143x over previous
; __device__ __forceinline__ void phase_nsa_cmp(const Params& p, u16* sm) {
;     ...
;     for (int qi = 0; qi < 4; ++qi) {
;       const int q = wave * 4 + qi, tq = t0 + q, cur = tq >> 6, n = lane;
;       const bool causal = (n <= cur);
;       const bool forced = (n == 0) || (n == cur) || (n == cur - 1);
;       const float sc = causal ? (Imp[q * 64 + n] + (forced ? 1e4f : 0.f)) : -1e30f;
;       int rank = 0;
;       Imp[q * 64 + n] = sc;
;       __builtin_amdgcn_wave_barrier();
; #pragma unroll 8
;       for (int n2 = 0; n2 < 64; ++n2) {
;         const float s2 = Imp[q * 64 + n2];
;         rank += ((s2 > sc) || (s2 == sc && n2 < n)) ? 1 : 0;
;       }
;       const unsigned long long mk = __ballot(causal && rank < 16);
;       if (lane == 0) p.msk[(size_t)(b * 2 + g) * SEQ + tq] = mk;
;     }
.Lrs0_begin:
	s_mov_b64 s[18:19], vcc
	s_bcnt1_i32_b64 s21, s[18:19]
	s_mov_b64 s[16:17], s[18:19]
	s_cmp_le_u32 s21, 16
	s_cbranch_scc1 .Lrs0_done
	s_mov_b64 s[16:17], 0
	s_mov_b32 s20, 16
	s_mov_b32 s27, 0x40000000
.Lrs0_bit:
	v_and_b32_e32 v3, s27, v2
	v_cmp_ne_u32_e64 s[22:23], 0, v3
	s_and_b64 s[22:23], s[22:23], s[18:19]
	s_bcnt1_i32_b64 s21, s[22:23]
	s_andn2_b64 s[24:25], s[18:19], s[22:23]
	s_or_b64 s[14:15], s[16:17], s[22:23]
	s_sub_u32 s26, s20, s21
	s_cmp_ge_u32 s21, s20
	s_cselect_b64 s[18:19], s[22:23], s[24:25]
	s_cselect_b64 s[16:17], s[16:17], s[14:15]
	s_cselect_b32 s20, s20, s26
	s_lshr_b32 s27, s27, 1
	s_cmp_lg_u32 s27, 0
	s_cbranch_scc1 .Lrs0_bit
.Lrs0_tie:
	s_ff1_i32_b64 s21, s[18:19]
	s_bitset1_b64 s[16:17], s21
	s_bitset0_b64 s[18:19], s21
	s_sub_u32 s20, s20, 1
	s_cmp_lg_u32 s20, 0
	s_cbranch_scc1 .Lrs0_tie
.Lrs0_done:
	v_ashrrev_i32_e32 v1, 31, v0
	s_and_saveexec_b64 s[14:15], s[4:5]
	s_cbranch_execz .LBB0_1257
	s_add_u32 s18, s58, s50
	s_addc_u32 s19, s59, 0
	v_lshl_add_u64 v[2:3], v[0:1], 3, s[18:19]
	v_mov_b64_e32 v[4:5], s[16:17]
	global_store_dwordx2 v[2:3], v[4:5], off

; __device__ __forceinline__ void phase_nsa_cmp(const Params& p, u16* sm) {
;     ...
;       const unsigned long long mk = __ballot(causal && rank < 16);
;       if (lane == 0) p.msk[(size_t)(b * 2 + g) * SEQ + tq] = mk;
.Lrs1_done:
	s_and_saveexec_b64 s[14:15], s[4:5]
	s_cbranch_execz .LBB0_1263
	s_add_u32 s18, s58, s50
	s_addc_u32 s19, s59, 0
	v_lshl_add_u64 v[2:3], v[0:1], 3, s[18:19]
	v_mov_b64_e32 v[4:5], s[16:17]
	global_store_dwordx2 v[2:3], v[4:5], off offset:8

; __device__ __forceinline__ void phase_nsa_cmp(const Params& p, u16* sm) {
;     ...
;       const unsigned long long mk = __ballot(causal && rank < 16);
;       if (lane == 0) p.msk[(size_t)(b * 2 + g) * SEQ + tq] = mk;
.Lrs2_done:
	s_and_saveexec_b64 s[14:15], s[4:5]
	s_cbranch_execz .LBB0_1269
	s_add_u32 s18, s58, s50
	s_addc_u32 s19, s59, 0
	v_lshl_add_u64 v[2:3], v[0:1], 3, s[18:19]
	v_mov_b64_e32 v[4:5], s[16:17]
	global_store_dwordx2 v[2:3], v[4:5], off offset:16

; __device__ __forceinline__ void phase_nsa_cmp(const Params& p, u16* sm) {
;     ...
;       const unsigned long long mk = __ballot(causal && rank < 16);
;       if (lane == 0) p.msk[(size_t)(b * 2 + g) * SEQ + tq] = mk;
.Lrs3_done:
	s_and_saveexec_b64 s[14:15], s[4:5]
	s_cbranch_execz .LBB0_1220
	s_add_u32 s18, s58, s50
	s_addc_u32 s19, s59, 0
	v_lshl_add_u64 v[0:1], v[0:1], 3, s[18:19]
	v_mov_b64_e32 v[2:3], s[16:17]
	global_store_dwordx2 v[0:1], v[2:3], off offset:24
	s_branch .LBB0_1220
.LBB0_1275:
	s_cmp_lt_i32 s75, 15
	s_cbranch_scc1 .LBB0_1319
	s_waitcnt vmcnt(0) lgkmcnt(0)
	s_barrier

; #define NSA_FETCH(rk, rv, e) do { const int v_ = lst[(e)]; \
;       const u16* kp_ = (v_ < 64) ? ksb + (size_t)v_ * 64 * 128 : kwb + (size_t)(v_ - 64) * 64 * 128; \
;       const u16* vp_ = (v_ < 64) ? vsb + v_ * 64 : vwb + (v_ - 64) * 64; \
;       rk = *(const uint4*)(kp_ + (size_t)pr * 128 + pc * 8); rv = *(const uint4*)(vp_ + (size_t)pr * SEQ + pc * 8); } while (0)
; __device__ __forceinline__ void phase_nsa_sw(const Params& p, u16* sm) {
;     ...
;   for (int tile = blockIdx.x; tile < ntiles; tile += gridDim.x) {
;     int qb = 127 - (tile >> 4), bg = tile & 15;
;     if (gridDim.x == 256) {
;       const int k = 7 - (tile >> 8), r = (int)blockIdx.x >> 4;
;       qb = 32 * (k >> 1) + ((k & 1) ? 31 - r : r);
;       bg = (int)blockIdx.x & 15;
;     }
;     const int b = bg >> 1, g = bg & 1;
;     const int t0 = qb * 32, myt = t0 + 16 * qh + fr;
;     const size_t tokbase = (size_t)b * SEQ;
;     const int hA = g * 8 + wq * 2;
;     bf16x8 qf[2][2];
; #pragma unroll
;     for (int hh = 0; hh < 2; ++hh)
; #pragma unroll
;       for (int ks = 0; ks < 2; ++ks)
;         qf[hh][ks] = *(const bf16x8*)(p.qn + (tokbase + myt) * DM + (hA + hh) * 64 + ks * 32 + fq * 8);
;     float gates[2][3];
; #pragma unroll
;     for (int hh = 0; hh < 2; ++hh)
; #pragma unroll
;       for (int r = 0; r < 3; ++r) gates[hh][r] = p.gbuf[(tokbase + myt) * 48 + (hA + hh) * 3 + r];
;     NsaState st;
;     f32x4 s[2][4];
;     const unsigned long long* mskp = p.msk + (size_t)(b * 2 + g) * SEQ + t0;
;     const unsigned long long mymask = mskp[16 * qh + fr];
;     unsigned long long um = 0;
; #pragma unroll
;     for (int q = 0; q < 32; ++q) um |= mskp[q];
;     const u16* ksb = p.ksb + tokbase * 128 + g * 64;
;     const u16* vsb = p.vsT + (size_t)(b * 2 + g) * 64 * SEQ;
;     const u16* kwb = p.kwb + tokbase * 128 + g * 64;
;     const u16* vwb = p.vwT + (size_t)(b * 2 + g) * 64 * SEQ;
;     const int kt_lo = (t0 >= 511) ? ((t0 - 511) >> 6) : 0, kt_hi = (t0 + 31) >> 6;
;     const int nsel = __popcll(um), ntl = nsel + (kt_hi - kt_lo + 1);
;     if (tid < 64) {
;       if ((um >> tid) & 1ull) lst[__popcll(um & ((1ull << tid) - 1ull))] = tid;
;       if (tid <= kt_hi - kt_lo) lst[nsel + tid] = 64 + kt_lo + tid;
;     ...
;     NSA_FETCH(rkA, rvA, 0);
.LBB0_1327:
	s_lshl_b32 s9, s8, 11
	s_and_b32 s13, s8, 15
	s_and_b32 s12, s8, 1
	s_lshl_b32 s44, s10, 5
	s_and_b32 s42, s9, 0x7000
	s_lshl_b32 s8, s13, 15
	s_add_u32 s11, s58, s8
	s_addc_u32 s14, s59, 0
	s_ashr_i32 s45, s44, 31
	s_lshl_b64 s[8:9], s[44:45], 3
	s_add_u32 s8, s11, s8
	s_addc_u32 s9, s14, s9
	s_lshl_b32 s15, s42, 8
	s_add_u32 s62, s3, s15
	s_addc_u32 s63, s76, 0
	s_lshl_b32 s15, s12, 7
	s_add_u32 s62, s62, s15
	s_addc_u32 s63, s63, 0
	s_lshl_b32 s15, s13, 19
	s_add_u32 s66, s85, s15
	s_addc_u32 s67, s86, 0
	v_readfirstlane_b32 s18, v251
	v_readfirstlane_b32 s19, v252
	s_nop 0
	s_mov_b32 m0, s18
	s_add_u32 s18, s18, 0x2400
	global_load_lds_dwordx4 v248, s[62:63]
	s_mov_b32 m0, s18
	s_cmp_ge_u32 s19, 0x2400
	global_load_lds_dwordx4 v249, s[66:67]
	s_cselect_b32 s16, s66, s62
	s_cselect_b32 s17, s67, s63
	s_mov_b32 m0, s19
	s_mov_b64 exec, 0xffff
	global_load_lds_dwordx4 v250, s[16:17]
	s_mov_b64 exec, -1
	global_load_dwordx4 v[20:23], v0, s[8:9]
	global_load_dwordx4 v[24:27], v0, s[8:9] offset:16
	global_load_dwordx4 v[28:31], v0, s[8:9] offset:32
	global_load_dwordx4 v[32:35], v0, s[8:9] offset:48
	global_load_dwordx4 v[36:39], v0, s[8:9] offset:64
	global_load_dwordx4 v[40:43], v0, s[8:9] offset:80
	global_load_dwordx4 v[44:47], v0, s[8:9] offset:96
	global_load_dwordx4 v[48:51], v0, s[8:9] offset:112
	global_load_dwordx4 v[52:55], v0, s[8:9] offset:128
	global_load_dwordx4 v[56:59], v0, s[8:9] offset:144
	global_load_dwordx4 v[60:63], v0, s[8:9] offset:176
	global_load_dwordx4 v[64:67], v0, s[8:9] offset:160
	v_add_u32_e32 v2, s44, v172
	v_lshl_or_b32 v1, s12, 3, v212
	v_ashrrev_i32_e32 v3, 31, v2
	global_load_dwordx4 v[68:71], v0, s[8:9] offset:208
	global_load_dwordx4 v[72:75], v0, s[8:9] offset:192
	v_lshlrev_b32_e32 v195, 6, v1
	v_lshl_add_u64 v[8:9], v[2:3], 0, s[42:43]
	v_or_b32_e32 v3, 64, v195
	v_lshlrev_b64 v[204:205], 11, v[8:9]
	v_mov_b32_e32 v5, v0
	v_mov_b32_e32 v203, v0
	v_lshlrev_b32_e32 v4, 7, v1
	v_mul_u32_u24_e32 v1, 3, v1
	v_lshlrev_b32_e32 v202, 1, v3
	v_mad_u64_u32 v[10:11], s[14:15], v8, s47, v[184:185]
	v_lshl_add_u64 v[12:13], v[180:181], 0, v[204:205]
	v_mov_b32_e32 v7, v0
	v_lshlrev_b32_e32 v6, 2, v1
	global_load_dwordx4 v[76:79], v0, s[8:9] offset:240
	global_load_dwordx4 v[80:83], v0, s[8:9] offset:224
	v_mad_i32_i24 v11, v9, s47, v11
	v_lshl_add_u64 v[8:9], v[12:13], 0, v[4:5]
	v_lshl_add_u64 v[16:17], v[12:13], 0, v[202:203]
	v_lshl_add_u64 v[84:85], v[10:11], 0, v[6:7]
	global_load_dwordx4 v[4:7], v[8:9], off
	s_nop 0
	global_load_dwordx4 v[8:11], v[8:9], off offset:64
	s_nop 0
	global_load_dwordx4 v[12:15], v[16:17], off
	s_nop 0
	global_load_dwordx4 v[16:19], v[16:17], off offset:64
	s_nop 0
	global_load_dwordx2 v[208:209], v[84:85], off offset:4
	global_load_dwordx2 v[206:207], v[84:85], off offset:16
	global_load_dwordx2 v[210:211], v175, s[8:9]
	s_add_i32 s8, s44, 0xfffffe01
	s_ashr_i32 s8, s8, 6
	s_cmp_gt_i32 s10, 15
	s_cselect_b32 s15, s8, 0
	s_ashr_i32 s45, s10, 1
	s_sub_i32 s14, s45, s15
	s_waitcnt vmcnt(0)
	v_or_b32_e32 v1, v22, v20
	v_or_b32_e32 v3, v23, v21
	v_or_b32_e32 v1, v1, v24
	v_or_b32_e32 v3, v3, v25
	v_or_b32_e32 v1, v1, v26
	v_or_b32_e32 v3, v3, v27
	v_or_b32_e32 v1, v1, v28
	v_or_b32_e32 v3, v3, v29
	v_or_b32_e32 v1, v1, v30
	v_or_b32_e32 v3, v3, v31
	v_or_b32_e32 v1, v1, v32
	v_or_b32_e32 v3, v3, v33
	v_or_b32_e32 v1, v1, v34
	v_or_b32_e32 v3, v3, v35
	v_or_b32_e32 v1, v1, v36
	v_or_b32_e32 v3, v3, v37
	v_or_b32_e32 v1, v1, v38
	v_or_b32_e32 v3, v3, v39
	v_or_b32_e32 v1, v1, v40
	v_or_b32_e32 v3, v3, v41
	v_or_b32_e32 v1, v1, v42
	v_or_b32_e32 v3, v3, v43
	v_or_b32_e32 v1, v1, v44
	v_or_b32_e32 v3, v3, v45
	v_or_b32_e32 v1, v1, v46
	v_or_b32_e32 v3, v3, v47
	v_or_b32_e32 v1, v1, v48
	v_or_b32_e32 v3, v3, v49
	v_or_b32_e32 v1, v1, v50
	v_or_b32_e32 v3, v3, v51
	v_or_b32_e32 v1, v1, v52
	v_or_b32_e32 v3, v3, v53
	v_or_b32_e32 v1, v1, v54
	v_or_b32_e32 v3, v3, v55
	v_or_b32_e32 v1, v1, v56
	v_or_b32_e32 v3, v3, v57
	v_or_b32_e32 v1, v1, v58
	v_or_b32_e32 v3, v3, v59
	v_or_b32_e32 v1, v1, v64
	v_or_b32_e32 v3, v3, v65
	v_or_b32_e32 v1, v1, v66
	v_or_b32_e32 v3, v3, v67
	v_or_b32_e32 v1, v1, v60
	v_or_b32_e32 v3, v3, v61
	v_or_b32_e32 v1, v1, v62
	v_or_b32_e32 v3, v3, v63
	v_or_b32_e32 v1, v1, v72
	v_or_b32_e32 v3, v3, v73
	v_or_b32_e32 v1, v1, v74
	v_or_b32_e32 v3, v3, v75
	v_or_b32_e32 v1, v1, v68
	v_or_b32_e32 v3, v3, v69
	v_or_b32_e32 v1, v1, v70
	v_or_b32_e32 v3, v3, v71
	v_or_b32_e32 v1, v1, v80
	v_or_b32_e32 v3, v3, v81
	v_or_b32_e32 v1, v1, v82
	v_or_b32_e32 v3, v3, v83
	v_or_b32_e32 v1, v1, v76
	v_or_b32_e32 v3, v3, v77
	v_or_b32_e32 v1, v1, v78
	v_or_b32_e32 v3, v3, v79
	v_bcnt_u32_b32 v20, v1, 0
	v_bcnt_u32_b32 v203, v3, v20
	s_and_saveexec_b64 s[8:9], s[4:5]
	s_cbranch_execz .LBB0_1332
	v_and_b32_e32 v21, v3, v177
	v_and_b32_e32 v20, v1, v176
	v_cmp_ne_u64_e32 vcc, 0, v[20:21]
	s_and_saveexec_b64 s[10:11], vcc
	s_cbranch_execz .LBB0_1330
	v_and_b32_e32 v1, v1, v178
	v_and_b32_e32 v3, v3, v173
	v_bcnt_u32_b32 v1, v1, 0
	v_bcnt_u32_b32 v1, v3, v1
	v_lshlrev_b32_e32 v1, 2, v1
	ds_write_b32 v1, v192 offset:36864

; __device__ __forceinline__ int rho_row(int k) { return (k & 32) | ((k & 4) << 2) | ((k & 24) >> 1) | (k & 3); }
; #define NSA_FETCH(rk, rv, e) do { const int v_ = lst[(e)]; \
;       const u16* kp_ = (v_ < 64) ? ksb + (size_t)v_ * 64 * 128 : kwb + (size_t)(v_ - 64) * 64 * 128; \
;       const u16* vp_ = (v_ < 64) ? vsb + v_ * 64 : vwb + (v_ - 64) * 64; \
;       rk = *(const uint4*)(kp_ + (size_t)pr * 128 + pc * 8); rv = *(const uint4*)(vp_ + (size_t)pr * SEQ + pc * 8); } while (0)
; #define NSA_PUT(rk, rv, buf) do { *(uint4*)(sK + (buf) * 2 * 64 * LDSP + prl * LDSP + pc * 8) = rk; \
;       *(uint4*)(sV + (buf) * 2 * 64 * LDSP + pr * LDSP + pc * 8) = rv; } while (0)
; __device__ __forceinline__ void phase_nsa_sw(const Params& p, u16* sm) {
;     ...
;     const u16* ksb = p.ksb + tokbase * 128 + g * 64;
;     const u16* vsb = p.vsT + (size_t)(b * 2 + g) * 64 * SEQ;
;     const u16* kwb = p.kwb + tokbase * 128 + g * 64;
;     const u16* vwb = p.vwT + (size_t)(b * 2 + g) * 64 * SEQ;
;     const int kt_lo = (t0 >= 511) ? ((t0 - 511) >> 6) : 0, kt_hi = (t0 + 31) >> 6;
;     const int nsel = __popcll(um), ntl = nsel + (kt_hi - kt_lo + 1);
;     if (tid < 64) {
;       if ((um >> tid) & 1ull) lst[__popcll(um & ((1ull << tid) - 1ull))] = tid;
;       if (tid <= kt_hi - kt_lo) lst[nsel + tid] = 64 + kt_lo + tid;
;     }
;     __syncthreads();
;     const int pc = tid & 7, pr = tid >> 3, prl = rho_row(pr);
;     uint4 rkA, rvA;
;     ...
;     NSA_FETCH(rkA, rvA, 0);
;     NSA_PUT(rkA, rvA, 0);
;     if (ntl > 1) NSA_FETCH(rkA, rvA, 1);
.LBB0_1332:
	s_or_b64 exec, exec, s[8:9]
	s_lshl_b32 s8, s42, 8
	s_add_u32 s9, s3, s8
	s_addc_u32 s10, s76, 0
	s_lshl_b32 s11, s12, 7
	s_add_u32 s62, s9, s11
	s_addc_u32 s63, s10, 0
	s_lshl_b32 s9, s13, 19
	s_add_u32 s66, s85, s9
	s_addc_u32 s67, s86, 0
	s_waitcnt lgkmcnt(0)
	s_barrier
	s_add_u32 s8, s77, s8
	s_addc_u32 s10, s84, 0
	s_add_u32 s78, s8, s11
	s_addc_u32 s79, s10, 0
	s_add_u32 s80, s87, s9
	s_addc_u32 s81, s88, 0
	v_add_u32_e32 v1, s14, v203
	v_add_u32_e32 v231, 1, v1
	v_and_b32_e32 v3, 63, v192
	v_lshlrev_b32_e32 v3, 2, v3
	ds_read_b32 v24, v3 offset:36864
	ds_read_b32 v25, v3 offset:37120
	v_readfirstlane_b32 s13, v1
	v_mov_b32_e32 v20, s48
	v_mov_b32_e32 v21, s48
	v_mov_b32_e32 v22, s48
	v_mov_b32_e32 v23, s48
	s_min_i32 s9, s13, 1
	s_min_i32 s10, s13, 2
	s_waitcnt lgkmcnt(0)
	v_readlane_b32 s9, v24, s9
	v_readlane_b32 s10, v24, s10
	s_movk_i32 s12, 0x4800
	s_cmp_lt_i32 s9, 64
	s_cselect_b32 s14, s62, s78
	s_cselect_b32 s15, s63, s79
	s_cselect_b32 s16, s66, s80
	s_cselect_b32 s17, s67, s81
	s_and_b32 s13, s9, 63
	s_lshl_b32 s18, s13, 14
	s_lshl_b32 s13, s13, 7
	s_add_u32 s14, s14, s18
	s_addc_u32 s15, s15, 0
	s_add_u32 s16, s16, s13
	s_addc_u32 s17, s17, 0
	v_readfirstlane_b32 s18, v251
	v_readfirstlane_b32 s19, v252
	s_nop 0
	s_add_u32 s18, s18, s12
	s_mov_b32 m0, s18
	s_add_u32 s18, s18, 0x2400
	global_load_lds_dwordx4 v248, s[14:15]
	s_mov_b32 m0, s18
	s_cmp_ge_u32 s19, 0x2400
	global_load_lds_dwordx4 v249, s[16:17]
	s_cselect_b32 s14, s16, s14
	s_cselect_b32 s15, s17, s15
	s_add_u32 s19, s19, s12
	s_mov_b32 m0, s19
	s_mov_b64 exec, 0xffff
	global_load_lds_dwordx4 v250, s[14:15]
	s_mov_b64 exec, -1
	s_mov_b32 s12, 0x12000
	s_cmp_lt_i32 s10, 64
	s_cselect_b32 s14, s62, s78
	s_cselect_b32 s15, s63, s79
	s_cselect_b32 s16, s66, s80
	s_cselect_b32 s17, s67, s81
	s_and_b32 s13, s10, 63
	s_lshl_b32 s18, s13, 14
	s_lshl_b32 s13, s13, 7
	s_add_u32 s14, s14, s18
	s_addc_u32 s15, s15, 0
	s_add_u32 s16, s16, s13
	s_addc_u32 s17, s17, 0
	v_readfirstlane_b32 s18, v251
	v_readfirstlane_b32 s19, v252
	s_nop 0
	s_add_u32 s18, s18, s12
	s_mov_b32 m0, s18
	s_add_u32 s18, s18, 0x2400
	global_load_lds_dwordx4 v248, s[14:15]
	s_mov_b32 m0, s18
	s_cmp_ge_u32 s19, 0x2400
	global_load_lds_dwordx4 v249, s[16:17]
	s_cselect_b32 s14, s16, s14
	s_cselect_b32 s15, s17, s15
	s_add_u32 s19, s19, s12
	s_mov_b32 m0, s19
	s_mov_b64 exec, 0xffff
	global_load_lds_dwordx4 v250, s[14:15]
	s_mov_b64 exec, -1
